# P0 weight transposes rewritten by hand: all 32 loads of an item in flight, next item prefetched, cvt_pk instead of bit trick
# speedup vs baseline: 1.0439x; 1.0439x over previous
; #define LAS __attribute__((address_space(3)))
; __device__ __forceinline__ void transpose_item(const float* W, const float* g  , int K, int N, bf16* WT, LAS float* scr, int kb, int nb, int lane) {
;     const int k0 = 64 * kb, n0 = 32 * nb;
; #pragma unroll 8
;     for (int i = 0; i < 32; ++i) { const int kk = 2 * i + (lane >> 5); const float gv = g ? g[k0 + kk] : 1.f; scr[kk * 33 + (lane & 31)] = W[(size_t)(k0 + kk) * N + n0 + (lane & 31)] * gv; }
; __global__ void __launch_bounds__(NWAVES * 64, 2) fwd(Args args) {
;     ...
;         transpose_tensor(ka->in[8], ka->in[4], 2 * DM, 2, DM, NQKV, WSB(WS_WQKVA), scr, gw, NGW, lane);
;         transpose_tensor(ka->in[13], ka->in[4] + DM, 2 * DM, 2, DM, 3 * NQKV, WSB(WS_WQKVB), scr, gw, NGW, lane);
;         transpose_tensor(ka->in[12], nullptr, 0, 2, DM, DM, WSB(WS_WOA), scr, gw, NGW, lane);
;         transpose_tensor(ka->in[17], nullptr, 0, 2, DM, DM, WSB(WS_WOB), scr, gw, NGW, lane);
;         transpose_tensor(ka->in[18], ka->in[5], DM, 4, DM, XHEAD * HD, WSB(WS_WQX), scr, gw, NGW, lane);
;         transpose_tensor(ka->in[19], nullptr, 0, 4, DM, 2 * XHEAD * HD, WSB(WS_WKVX), scr, gw, NGW, lane);
;         transpose_tensor(ka->in[22], nullptr, 0, 4, XHEAD * HD, DM, WSB(WS_WOX), scr, gw, NGW, lane);
;         transpose_tensor(ka->in[23], ka->in[7], DM, 4, DM, DFF, WSB(WS_WUP), scr, gw, NGW, lane);
;         transpose_tensor(ka->in[24], nullptr, 0, 4, DFF, DM, WSB(WS_WDN), scr, gw, NGW, lane);
.LBB0_13:
.LBB0_14:
	v_readlane_b32 s10, v252, 0
	v_readlane_b32 s11, v252, 1
	v_lshrrev_b32_e32 v100, 6, v0
	v_and_b32_e32 v101, 63, v0
	s_load_dwordx2 s[12:13], s[10:11], 0xd0
	v_readfirstlane_b32 s14, v100
	v_lshrrev_b32_e32 v102, 5, v101
	v_and_b32_e32 v103, 31, v101
	v_and_b32_e32 v105, 7, v101
	v_lshrrev_b32_e32 v106, 3, v101
	s_lshl_b32 s15, s59, 3
	s_add_i32 s15, s15, s14
	s_lshl_b32 s16, s60, 3
	s_lshl_b32 s17, s14, 14
	v_mad_u32_u24 v104, v102, 33, v103
	v_lshl_add_u32 v104, v104, 2, s17
	v_mul_u32_u24_e32 v107, 0x108, v105
	v_add_u32_e32 v107, v107, v106
	v_lshl_add_u32 v107, v107, 2, s17
	v_lshlrev_b32_e32 v108, 5, v105
	v_lshlrev_b32_e32 v109, 2, v103
	v_lshlrev_b32_e32 v105, 4, v105
	s_mov_b32 s18, 0
	s_waitcnt lgkmcnt(0)
.Lwt_dispatch:
	s_cmp_eq_u32 s18, 0
	s_cbranch_scc1 .Lwt_p0
	s_cmp_eq_u32 s18, 1
	s_cbranch_scc1 .Lwt_p1
	s_cmp_eq_u32 s18, 2
	s_cbranch_scc1 .Lwt_p2
	s_cmp_eq_u32 s18, 3
	s_cbranch_scc1 .Lwt_p3
	s_cmp_eq_u32 s18, 4
	s_cbranch_scc1 .Lwt_p4
	s_cmp_eq_u32 s18, 5
	s_cbranch_scc1 .Lwt_p5
	s_cmp_eq_u32 s18, 6
	s_cbranch_scc1 .Lwt_p6
	s_cmp_eq_u32 s18, 7
	s_cbranch_scc1 .Lwt_p7
	s_cmp_eq_u32 s18, 8
	s_cbranch_scc1 .Lwt_p8
	s_branch .Lwt_end
.Lwt_p0:
	s_movk_i32 s19, 0x40
	s_mov_b32 s62, 0x800
	s_mov_b32 s63, 0x1800
	s_mov_b32 s64, 2
	s_mov_b32 s26, 0xaaaab
	s_mov_b32 s28, 0x1555556
	s_mov_b32 s34, 0x1000000
	s_movk_i32 s20, 0x20
	s_mov_b32 s21, 0x0
	s_mov_b32 s22, 0x4000
	s_mov_b32 s23, 1
	s_branch .Lwt_run
.Lwt_p1:
	s_movk_i32 s19, 0x68
	s_mov_b32 s62, 0x800
	s_mov_b32 s63, 0x4800
	s_mov_b32 s64, 2
	s_mov_b32 s26, 0x38e39
	s_mov_b32 s28, 0x71c71d
	s_mov_b32 s34, 0x4000000
	s_movk_i32 s20, 0x20
	s_mov_b32 s21, 0x2000
	s_mov_b32 s22, 0x4000
	s_mov_b32 s23, 1
	s_branch .Lwt_run
.Lwt_p2:
	s_movk_i32 s19, 0x60
	s_mov_b32 s62, 0x800
	s_mov_b32 s63, 0x800
	s_mov_b32 s64, 2
	s_mov_b32 s26, 0x200000
	s_mov_b32 s28, 0x4000000
	s_mov_b32 s34, 0xd000000
	s_movk_i32 s20, 0x20
	s_mov_b32 s21, 0
	s_mov_b32 s22, 0
	s_mov_b32 s23, 0
	s_branch .Lwt_run
.Lwt_p3:
	s_movk_i32 s19, 0x88
	s_mov_b32 s62, 0x800
	s_mov_b32 s63, 0x800
	s_mov_b32 s64, 2
	s_mov_b32 s26, 0x200000
	s_mov_b32 s28, 0x4000000
	s_mov_b32 s34, 0xe000000
	s_movk_i32 s20, 0x20
	s_mov_b32 s21, 0
	s_mov_b32 s22, 0
	s_mov_b32 s23, 0
	s_branch .Lwt_run
.Lwt_p4:
	s_movk_i32 s19, 0x90
	s_mov_b32 s62, 0x800
	s_mov_b32 s63, 0x200
	s_mov_b32 s64, 4
	s_mov_b32 s26, 0x800000
	s_mov_b32 s28, 0x10000000
	s_mov_b32 s34, 0xf000000
	s_movk_i32 s20, 0x28
	s_mov_b32 s21, 0x0
	s_mov_b32 s22, 0x2000
	s_mov_b32 s23, 1
	s_branch .Lwt_run
.Lwt_p5:
	s_movk_i32 s19, 0x98
	s_mov_b32 s62, 0x800
	s_mov_b32 s63, 0x400
	s_mov_b32 s64, 4
	s_mov_b32 s26, 0x400000
	s_mov_b32 s28, 0x8000000
	s_mov_b32 s34, 0xf800000
	s_movk_i32 s20, 0x20
	s_mov_b32 s21, 0
	s_mov_b32 s22, 0
	s_mov_b32 s23, 0
	s_branch .Lwt_run
.Lwt_p6:
	s_movk_i32 s19, 0xb0
	s_mov_b32 s62, 0x200
	s_mov_b32 s63, 0x800
	s_mov_b32 s64, 4
	s_mov_b32 s26, 0x800000
	s_mov_b32 s28, 0x4000000
	s_mov_b32 s34, 0x10800000
	s_movk_i32 s20, 0x20
	s_mov_b32 s21, 0
	s_mov_b32 s22, 0
	s_mov_b32 s23, 0
	s_branch .Lwt_run
.Lwt_p7:
	s_movk_i32 s19, 0xb8
	s_mov_b32 s62, 0x800
	s_mov_b32 s63, 0x2000
	s_mov_b32 s64, 4
	s_mov_b32 s26, 0x80000
	s_mov_b32 s28, 0x1000000
	s_mov_b32 s34, 0x11000000
	s_movk_i32 s20, 0x38
	s_mov_b32 s21, 0x0
	s_mov_b32 s22, 0x2000
	s_mov_b32 s23, 1
	s_branch .Lwt_run
.Lwt_p8:
	s_movk_i32 s19, 0xc0
	s_mov_b32 s62, 0x2000
	s_mov_b32 s63, 0x800
	s_mov_b32 s64, 4
	s_mov_b32 s26, 0x80000
	s_mov_b32 s28, 0x4000000
	s_mov_b32 s34, 0x19000000
	s_movk_i32 s20, 0x20
	s_mov_b32 s21, 0
	s_mov_b32 s22, 0
	s_mov_b32 s23, 0
	s_branch .Lwt_run
; #define GAS __attribute__((address_space(1)))
; #define LAS __attribute__((address_space(3)))
; #define LDS_WAIT() asm volatile("s_waitcnt lgkmcnt(0)" ::: "memory")
; __device__ __forceinline__ unsigned pk2(float lo, float hi) { return f2bf(lo) | (f2bf(hi) << 16); }
; __device__ __forceinline__ void transpose_item(const float* W, const float* g  , int K, int N, bf16* WT, LAS float* scr, int kb, int nb, int lane) {
;     const int k0 = 64 * kb, n0 = 32 * nb;
; #pragma unroll 8
;     for (int i = 0; i < 32; ++i) { const int kk = 2 * i + (lane >> 5); const float gv = g ? g[k0 + kk] : 1.f; scr[kk * 33 + (lane & 31)] = W[(size_t)(k0 + kk) * N + n0 + (lane & 31)] * gv; }
;     LDS_WAIT(); asm volatile("" ::: "memory");
;     const int c = lane & 7;
; #pragma unroll
;     for (int j = 0; j < 4; ++j) { const int n = (lane >> 3) + 8 * j; const LAS float* s = scr + (8 * c) * 33 + n;
;         v4u o; o.x = pk2(s[0 * 33], s[1 * 33]); o.y = pk2(s[2 * 33], s[3 * 33]); o.z = pk2(s[4 * 33], s[5 * 33]); o.w = pk2(s[6 * 33], s[7 * 33]);
;         *(GAS v4u*)(WT + (size_t)(n0 + n) * K + k0 + 8 * c) = o; }
;     LDS_WAIT(); asm volatile("" ::: "memory");
; }
; __device__ __forceinline__ void transpose_tensor(const float* W, const float* g, int gstep, int nl, int K, int N, bf16* WT, LAS float* scr, int gw, int NGW, int lane) {
;     const int nblk = N / 32, per = (K / 64) * nblk, total = nl * per;
;     for (int it = gw; it < total; it += NGW) { const int l = it / per, r = it - l * per;
;         transpose_item(W + (size_t)l * K * N, g ? g + (size_t)l * gstep : nullptr, K, N, WT + (size_t)l * K * N, scr, r / nblk, r % nblk, lane); }
.Lwt_run:
	s_load_dwordx2 s[38:39], s[10:11], s19
	s_load_dwordx2 s[40:41], s[10:11], s20
	s_lshr_b32 s27, s63, 5
	s_lshr_b32 s25, s62, 6
	s_mul_i32 s25, s25, s27
	s_mul_i32 s24, s25, s64
	s_lshl_b32 s30, s63, 8
	s_mul_i32 s29, s62, s63
	s_lshl_b32 s31, s29, 1
	s_lshl_b32 s29, s29, 2
	s_lshl_b32 s32, s62, 6
	s_lshl_b32 s35, s63, 2
	s_lshl_b32 s36, s62, 1
	s_add_u32 s42, s12, s34
	s_addc_u32 s43, s13, 0
	v_mad_u32_u24 v110, v102, s35, v109
	s_lshl_b32 s61, s35, 1
	v_add_u32_e32 v111, s61, v110
	v_add_u32_e32 v112, s61, v111
	v_add_u32_e32 v113, s61, v112
	v_add_u32_e32 v114, s61, v113
	v_add_u32_e32 v115, s61, v114
	v_add_u32_e32 v116, s61, v115
	v_add_u32_e32 v117, s61, v116
	v_add_u32_e32 v118, s61, v117
	v_add_u32_e32 v119, s61, v118
	v_add_u32_e32 v120, s61, v119
	v_add_u32_e32 v121, s61, v120
	v_add_u32_e32 v122, s61, v121
	v_add_u32_e32 v123, s61, v122
	v_add_u32_e32 v124, s61, v123
	v_add_u32_e32 v125, s61, v124
	v_add_u32_e32 v126, s61, v125
	v_add_u32_e32 v127, s61, v126
	v_add_u32_e32 v128, s61, v127
	v_add_u32_e32 v129, s61, v128
	v_add_u32_e32 v130, s61, v129
	v_add_u32_e32 v131, s61, v130
	v_add_u32_e32 v132, s61, v131
	v_add_u32_e32 v133, s61, v132
	v_add_u32_e32 v134, s61, v133
	v_add_u32_e32 v135, s61, v134
	v_add_u32_e32 v136, s61, v135
	v_add_u32_e32 v137, s61, v136
	v_add_u32_e32 v138, s61, v137
	v_add_u32_e32 v139, s61, v138
	v_add_u32_e32 v140, s61, v139
	v_add_u32_e32 v141, s61, v140
	v_mad_u32_u24 v142, v106, s36, v105
	s_lshl_b32 s61, s36, 3
	v_add_u32_e32 v143, s61, v142
	v_add_u32_e32 v144, s61, v143
	v_add_u32_e32 v145, s61, v144
	v_mov_b32_e32 v178, 1.0
	v_mov_b32_e32 v179, 1.0
	v_mov_b32_e32 v180, 1.0
	v_mov_b32_e32 v181, 1.0
	v_mov_b32_e32 v182, 1.0
	v_mov_b32_e32 v183, 1.0
	v_mov_b32_e32 v184, 1.0
	v_mov_b32_e32 v185, 1.0
	s_mov_b32 s37, s15
	s_waitcnt lgkmcnt(0)
	s_add_u32 s40, s40, s21
	s_addc_u32 s41, s41, 0
	s_cmp_lt_u32 s37, s24
	s_cbranch_scc0 .Lwt_next
	s_mul_hi_u32 s54, s37, s26
	s_mul_i32 s55, s54, s25
	s_sub_u32 s55, s37, s55
	s_mul_hi_u32 s56, s55, s28
	s_mul_i32 s57, s56, s27
	s_sub_u32 s57, s55, s57
	s_mul_i32 s58, s54, s29
	s_mul_i32 s61, s56, s30
	s_add_u32 s58, s58, s61
	s_lshl_b32 s61, s57, 7
	s_add_u32 s58, s58, s61
	s_add_u32 s44, s38, s58
	s_addc_u32 s45, s39, 0
	s_mul_i32 s58, s54, s31
	s_mul_i32 s61, s57, s32
	s_add_u32 s58, s58, s61
	s_lshl_b32 s61, s56, 7
	s_add_u32 s58, s58, s61
	s_add_u32 s50, s42, s58
	s_addc_u32 s51, s43, 0
	s_mul_i32 s58, s54, s22
	s_lshl_b32 s61, s56, 8
	s_add_u32 s58, s58, s61
	s_add_u32 s48, s40, s58
	s_addc_u32 s49, s41, 0
	global_load_dword v146, v110, s[44:45]
	global_load_dword v147, v111, s[44:45]
	global_load_dword v148, v112, s[44:45]
	global_load_dword v149, v113, s[44:45]
	global_load_dword v150, v114, s[44:45]
	global_load_dword v151, v115, s[44:45]
	global_load_dword v152, v116, s[44:45]
	global_load_dword v153, v117, s[44:45]
	global_load_dword v154, v118, s[44:45]
	global_load_dword v155, v119, s[44:45]
	global_load_dword v156, v120, s[44:45]
	global_load_dword v157, v121, s[44:45]
	global_load_dword v158, v122, s[44:45]
	global_load_dword v159, v123, s[44:45]
	global_load_dword v160, v124, s[44:45]
	global_load_dword v161, v125, s[44:45]
	global_load_dword v162, v126, s[44:45]
	global_load_dword v163, v127, s[44:45]
	global_load_dword v164, v128, s[44:45]
	global_load_dword v165, v129, s[44:45]
	global_load_dword v166, v130, s[44:45]
	global_load_dword v167, v131, s[44:45]
	global_load_dword v168, v132, s[44:45]
	global_load_dword v169, v133, s[44:45]
	global_load_dword v170, v134, s[44:45]
	global_load_dword v171, v135, s[44:45]
	global_load_dword v172, v136, s[44:45]
	global_load_dword v173, v137, s[44:45]
	global_load_dword v174, v138, s[44:45]
	global_load_dword v175, v139, s[44:45]
	global_load_dword v176, v140, s[44:45]
	global_load_dword v177, v141, s[44:45]
	s_cmp_eq_u32 s23, 0
	s_cbranch_scc1 .Lwt_nog_a
	global_load_dwordx4 v[178:181], v108, s[48:49]
	global_load_dwordx4 v[182:185], v108, s[48:49] offset:16

; #define LAS __attribute__((address_space(3)))
; #define LDS_WAIT() asm volatile("s_waitcnt lgkmcnt(0)" ::: "memory")
; __device__ __forceinline__ void transpose_item(const float* W, const float* g  , int K, int N, bf16* WT, LAS float* scr, int kb, int nb, int lane) {
;     ...
;     for (int i = 0; i < 32; ++i) { const int kk = 2 * i + (lane >> 5); const float gv = g ? g[k0 + kk] : 1.f; scr[kk * 33 + (lane & 31)] = W[(size_t)(k0 + kk) * N + n0 + (lane & 31)] * gv; }
;     LDS_WAIT(); asm volatile("" ::: "memory");
; __device__ __forceinline__ void transpose_tensor(const float* W, const float* g, int gstep, int nl, int K, int N, bf16* WT, LAS float* scr, int gw, int NGW, int lane) {
;     const int nblk = N / 32, per = (K / 64) * nblk, total = nl * per;
;     for (int it = gw; it < total; it += NGW) { const int l = it / per, r = it - l * per;
;         transpose_item(W + (size_t)l * K * N, g ? g + (size_t)l * gstep : nullptr, K, N, WT + (size_t)l * K * N, scr, r / nblk, r % nblk, lane); }
.Lwt_loop:
	v_mov_b32_e32 v186, v178
	v_mov_b32_e32 v187, v179
	v_mov_b32_e32 v188, v180
	v_mov_b32_e32 v189, v181
	v_mov_b32_e32 v190, v182
	v_mov_b32_e32 v191, v183
	v_mov_b32_e32 v192, v184
	v_mov_b32_e32 v193, v185
	ds_write_b32 v104, v146
	ds_write_b32 v104, v147 offset:264
	ds_write_b32 v104, v148 offset:528
	ds_write_b32 v104, v149 offset:792
	ds_write_b32 v104, v150 offset:1056
	ds_write_b32 v104, v151 offset:1320
	ds_write_b32 v104, v152 offset:1584
	ds_write_b32 v104, v153 offset:1848
	ds_write_b32 v104, v154 offset:2112
	ds_write_b32 v104, v155 offset:2376
	ds_write_b32 v104, v156 offset:2640
	ds_write_b32 v104, v157 offset:2904
	ds_write_b32 v104, v158 offset:3168
	ds_write_b32 v104, v159 offset:3432
	ds_write_b32 v104, v160 offset:3696
	ds_write_b32 v104, v161 offset:3960
	ds_write_b32 v104, v162 offset:4224
	ds_write_b32 v104, v163 offset:4488
	ds_write_b32 v104, v164 offset:4752
	ds_write_b32 v104, v165 offset:5016
	ds_write_b32 v104, v166 offset:5280
	ds_write_b32 v104, v167 offset:5544
	ds_write_b32 v104, v168 offset:5808
	ds_write_b32 v104, v169 offset:6072
	ds_write_b32 v104, v170 offset:6336
	ds_write_b32 v104, v171 offset:6600
	ds_write_b32 v104, v172 offset:6864
	ds_write_b32 v104, v173 offset:7128
	ds_write_b32 v104, v174 offset:7392
	ds_write_b32 v104, v175 offset:7656
	ds_write_b32 v104, v176 offset:7920
	ds_write_b32 v104, v177 offset:8184
	s_mov_b64 s[52:53], s[50:51]
	s_add_u32 s37, s37, s16
	s_cmp_lt_u32 s37, s24
	s_cbranch_scc0 .Lwt_noissue
	s_waitcnt lgkmcnt(0)
	s_mul_hi_u32 s54, s37, s26
	s_mul_i32 s55, s54, s25
	s_sub_u32 s55, s37, s55
	s_mul_hi_u32 s56, s55, s28
	s_mul_i32 s57, s56, s27
	s_sub_u32 s57, s55, s57
	s_mul_i32 s58, s54, s29
	s_mul_i32 s61, s56, s30
	s_add_u32 s58, s58, s61
	s_lshl_b32 s61, s57, 7
	s_add_u32 s58, s58, s61
	s_add_u32 s44, s38, s58
	s_addc_u32 s45, s39, 0
	s_mul_i32 s58, s54, s31
	s_mul_i32 s61, s57, s32
	s_add_u32 s58, s58, s61
	s_lshl_b32 s61, s56, 7
	s_add_u32 s58, s58, s61
	s_add_u32 s50, s42, s58
	s_addc_u32 s51, s43, 0
	s_mul_i32 s58, s54, s22
	s_lshl_b32 s61, s56, 8
	s_add_u32 s58, s58, s61
	s_add_u32 s48, s40, s58
	s_addc_u32 s49, s41, 0
	global_load_dword v146, v110, s[44:45]
	global_load_dword v147, v111, s[44:45]
	global_load_dword v148, v112, s[44:45]
	global_load_dword v149, v113, s[44:45]
	global_load_dword v150, v114, s[44:45]
	global_load_dword v151, v115, s[44:45]
	global_load_dword v152, v116, s[44:45]
	global_load_dword v153, v117, s[44:45]
	global_load_dword v154, v118, s[44:45]
	global_load_dword v155, v119, s[44:45]
	global_load_dword v156, v120, s[44:45]
	global_load_dword v157, v121, s[44:45]
	global_load_dword v158, v122, s[44:45]
	global_load_dword v159, v123, s[44:45]
	global_load_dword v160, v124, s[44:45]
	global_load_dword v161, v125, s[44:45]
	global_load_dword v162, v126, s[44:45]
	global_load_dword v163, v127, s[44:45]
	global_load_dword v164, v128, s[44:45]
	global_load_dword v165, v129, s[44:45]
	global_load_dword v166, v130, s[44:45]
	global_load_dword v167, v131, s[44:45]
	global_load_dword v168, v132, s[44:45]
	global_load_dword v169, v133, s[44:45]
	global_load_dword v170, v134, s[44:45]
	global_load_dword v171, v135, s[44:45]
	global_load_dword v172, v136, s[44:45]
	global_load_dword v173, v137, s[44:45]
	global_load_dword v174, v138, s[44:45]
	global_load_dword v175, v139, s[44:45]
	global_load_dword v176, v140, s[44:45]
	global_load_dword v177, v141, s[44:45]
	s_cmp_eq_u32 s23, 0
	s_cbranch_scc1 .Lwt_nog_b
	global_load_dwordx4 v[178:181], v108, s[48:49]
	global_load_dwordx4 v[182:185], v108, s[48:49] offset:16
; #define GAS __attribute__((address_space(1)))
; #define LAS __attribute__((address_space(3)))
; #define LDS_WAIT() asm volatile("s_waitcnt lgkmcnt(0)" ::: "memory")
; __device__ __forceinline__ unsigned pk2(float lo, float hi) { return f2bf(lo) | (f2bf(hi) << 16); }
; __device__ __forceinline__ void transpose_item(const float* W, const float* g  , int K, int N, bf16* WT, LAS float* scr, int kb, int nb, int lane) {
;     ...
;     const int c = lane & 7;
; #pragma unroll
;     for (int j = 0; j < 4; ++j) { const int n = (lane >> 3) + 8 * j; const LAS float* s = scr + (8 * c) * 33 + n;
;         v4u o; o.x = pk2(s[0 * 33], s[1 * 33]); o.y = pk2(s[2 * 33], s[3 * 33]); o.z = pk2(s[4 * 33], s[5 * 33]); o.w = pk2(s[6 * 33], s[7 * 33]);
;         *(GAS v4u*)(WT + (size_t)(n0 + n) * K + k0 + 8 * c) = o; }
;     LDS_WAIT(); asm volatile("" ::: "memory");
; }
; __device__ __forceinline__ void transpose_tensor(const float* W, const float* g, int gstep, int nl, int K, int N, bf16* WT, LAS float* scr, int gw, int NGW, int lane) {
;     const int nblk = N / 32, per = (K / 64) * nblk, total = nl * per;
;     for (int it = gw; it < total; it += NGW) { const int l = it / per, r = it - l * per;
;         transpose_item(W + (size_t)l * K * N, g ? g + (size_t)l * gstep : nullptr, K, N, WT + (size_t)l * K * N, scr, r / nblk, r % nblk, lane); }
; __global__ void __launch_bounds__(NWAVES * 64, 2) fwd(Args args) {
;     ...
;         for (int t = gw; t < 4 * MEMROWS; t += NGW) { const int i = t / MEMROWS, r = t - i * MEMROWS;
;             const float* mr = r < NMEM ? mem_prompt + (size_t)r * DM : mem_sample + (size_t)(r - NMEM) * DM;
;             rms_row_to_bf16(mr, g_mem + i * DM, MEMN + (size_t)t * DM, lane); }
.Lwt_nog_b:
.Lwt_noissue:
	s_waitcnt lgkmcnt(0)
	ds_read2_b32 v[194:195], v107 offset0:0 offset1:33
	ds_read2_b32 v[196:197], v107 offset0:66 offset1:99
	ds_read2_b32 v[198:199], v107 offset0:132 offset1:165
	ds_read2_b32 v[200:201], v107 offset0:198 offset1:231
	ds_read2_b32 v[202:203], v107 offset0:8 offset1:41
	ds_read2_b32 v[204:205], v107 offset0:74 offset1:107
	ds_read2_b32 v[206:207], v107 offset0:140 offset1:173
	ds_read2_b32 v[208:209], v107 offset0:206 offset1:239
	ds_read2_b32 v[210:211], v107 offset0:16 offset1:49
	ds_read2_b32 v[212:213], v107 offset0:82 offset1:115
	ds_read2_b32 v[214:215], v107 offset0:148 offset1:181
	ds_read2_b32 v[216:217], v107 offset0:214 offset1:247
	ds_read2_b32 v[218:219], v107 offset0:24 offset1:57
	ds_read2_b32 v[220:221], v107 offset0:90 offset1:123
	ds_read2_b32 v[222:223], v107 offset0:156 offset1:189
	ds_read2_b32 v[224:225], v107 offset0:222 offset1:255
	s_waitcnt lgkmcnt(15)
	v_mul_f32_e32 v194, v186, v194
	v_mul_f32_e32 v195, v187, v195
	v_cvt_pk_bf16_f32 v226, v194, v195
	s_waitcnt lgkmcnt(14)
	v_mul_f32_e32 v196, v188, v196
	v_mul_f32_e32 v197, v189, v197
	v_cvt_pk_bf16_f32 v227, v196, v197
	s_waitcnt lgkmcnt(13)
	v_mul_f32_e32 v198, v190, v198
	v_mul_f32_e32 v199, v191, v199
	v_cvt_pk_bf16_f32 v228, v198, v199
	s_waitcnt lgkmcnt(12)
	v_mul_f32_e32 v200, v192, v200
	v_mul_f32_e32 v201, v193, v201
	v_cvt_pk_bf16_f32 v229, v200, v201
	global_store_dwordx4 v142, v[226:229], s[52:53]
	s_waitcnt lgkmcnt(11)
	v_mul_f32_e32 v202, v186, v202
	v_mul_f32_e32 v203, v187, v203
	v_cvt_pk_bf16_f32 v230, v202, v203
	s_waitcnt lgkmcnt(10)
	v_mul_f32_e32 v204, v188, v204
	v_mul_f32_e32 v205, v189, v205
	v_cvt_pk_bf16_f32 v231, v204, v205
	s_waitcnt lgkmcnt(9)
	v_mul_f32_e32 v206, v190, v206
	v_mul_f32_e32 v207, v191, v207
	v_cvt_pk_bf16_f32 v232, v206, v207
	s_waitcnt lgkmcnt(8)
	v_mul_f32_e32 v208, v192, v208
	v_mul_f32_e32 v209, v193, v209
	v_cvt_pk_bf16_f32 v233, v208, v209
	global_store_dwordx4 v143, v[230:233], s[52:53]
	s_waitcnt lgkmcnt(7)
	v_mul_f32_e32 v210, v186, v210
	v_mul_f32_e32 v211, v187, v211
	v_cvt_pk_bf16_f32 v234, v210, v211
	s_waitcnt lgkmcnt(6)
	v_mul_f32_e32 v212, v188, v212
	v_mul_f32_e32 v213, v189, v213
	v_cvt_pk_bf16_f32 v235, v212, v213
	s_waitcnt lgkmcnt(5)
	v_mul_f32_e32 v214, v190, v214
	v_mul_f32_e32 v215, v191, v215
	v_cvt_pk_bf16_f32 v236, v214, v215
	s_waitcnt lgkmcnt(4)
	v_mul_f32_e32 v216, v192, v216
	v_mul_f32_e32 v217, v193, v217
	v_cvt_pk_bf16_f32 v237, v216, v217
	global_store_dwordx4 v144, v[234:237], s[52:53]
	s_waitcnt lgkmcnt(3)
	v_mul_f32_e32 v218, v186, v218
	v_mul_f32_e32 v219, v187, v219
	v_cvt_pk_bf16_f32 v238, v218, v219
	s_waitcnt lgkmcnt(2)
	v_mul_f32_e32 v220, v188, v220
	v_mul_f32_e32 v221, v189, v221
	v_cvt_pk_bf16_f32 v239, v220, v221
	s_waitcnt lgkmcnt(1)
	v_mul_f32_e32 v222, v190, v222
	v_mul_f32_e32 v223, v191, v223
	v_cvt_pk_bf16_f32 v240, v222, v223
	s_waitcnt lgkmcnt(0)
	v_mul_f32_e32 v224, v192, v224
	v_mul_f32_e32 v225, v193, v225
	v_cvt_pk_bf16_f32 v241, v224, v225
	global_store_dwordx4 v145, v[238:241], s[52:53]
	s_cmp_lt_u32 s37, s24
	s_cbranch_scc0 .Lwt_next
	s_waitcnt vmcnt(4)
	s_branch .Lwt_loop
.Lwt_next:
	s_add_u32 s18, s18, 1
	s_branch .Lwt_dispatch
.Lwt_end:
	s_waitcnt lgkmcnt(0)
	v_readlane_b32 s16, v252, 0
	v_readlane_b32 s17, v252, 1
	v_mov_b32_e32 v44, v0
	s_load_dwordx2 s[6:7], s[16:17], 0xd0
	s_load_dwordx2 s[8:9], s[16:17], 0x20
	v_readfirstlane_b32 s4, v44
	s_ashr_i32 s4, s4, 6
	s_lshl_b32 s5, s59, 3
	s_lshl_b32 s13, s4, 14
	s_add_i32 s12, s4, s5
	s_lshl_b32 s14, s60, 3
	s_add_i32 s15, s13, 0
	v_lshlrev_b32_e32 v3, 3, v44
	s_waitcnt lgkmcnt(0)
	s_cmp_eq_u64 s[8:9], 0
	v_bfe_u32 v34, v44, 3, 3
	v_and_b32_e32 v3, 56, v3
	s_cselect_b64 s[18:19], -1, 0
	s_cmp_lg_u64 s[8:9], 0
	v_bfe_u32 v2, v44, 5, 1
	v_and_b32_e32 v1, 31, v44
	v_mul_u32_u24_e32 v4, 0x84, v3
	v_lshlrev_b32_e32 v6, 2, v34
	s_cselect_b64 s[10:11], -1, 0
	s_cmpk_gt_i32 s12, 0x2fff
	v_mov_b32_e32 v5, 0
	s_movk_i32 s4, 0x84
	v_add3_u32 v35, s15, v4, v6
	v_or_b32_e32 v36, 8, v34
	v_or_b32_e32 v37, 16, v34
	v_or_b32_e32 v38, 24, v34
	v_lshlrev_b32_e32 v6, 2, v1
	v_or_b32_e32 v39, 14, v2
	v_or_b32_e32 v40, 12, v2
	v_or_b32_e32 v41, 10, v2
	v_or_b32_e32 v42, 8, v2
	v_or_b32_e32 v43, 6, v2
	v_or_b32_e32 v45, 4, v2
	v_or_b32_e32 v46, 2, v2
	v_lshlrev_b32_e32 v4, 1, v3
.LBB0_35:
	s_cmp_gt_i32 s12, 0x8fff
.LBB0_56:
	s_cmpk_lt_i32 s12, 0x1000
	s_cselect_b64 s[8:9], -1, 0
	s_cmpk_gt_i32 s12, 0xfff
	v_lshl_add_u32 v8, v1, 2, s15
.LBB0_65:
	s_cmpk_lt_i32 s12, 0x800
	s_cselect_b64 s[10:11], -1, 0
	s_cmpk_gt_i32 s12, 0x7ff
.LBB0_86:
	s_andn2_b64 vcc, exec, s[8:9]
.LBB0_91:
	s_andn2_b64 vcc, exec, s[10:11]
.LBB0_96:
	v_and_b32_e32 v47, 63, v44
	s_cmpk_gt_i32 s12, 0x7fff
	s_movk_i32 s15, 0x7fff
.LBB0_121:
	s_cmpk_gt_i32 s12, 0x13ff
	v_mov_b32_e32 v35, 0
	v_lshlrev_b32_e32 v34, 4, v47
	v_mbcnt_lo_u32_b32 v1, -1, 0
	v_lshlrev_b32_e32 v36, 3, v47
	s_cbranch_scc1 .LBB0_124
	v_mbcnt_hi_u32_b32 v2, -1, v1
	v_and_b32_e32 v3, 64, v2
	v_add_u32_e32 v3, 64, v3
	v_xor_b32_e32 v4, 1, v2
	v_cmp_lt_i32_e32 vcc, v4, v3
	s_load_dwordx2 s[4:5], s[16:17], 0x30
	s_load_dwordx4 s[8:11], s[16:17], 0x10
	v_cndmask_b32_e32 v4, v2, v4, vcc
	v_lshlrev_b32_e32 v45, 2, v4
	v_xor_b32_e32 v4, 2, v2
	v_cmp_lt_i32_e32 vcc, v4, v3
	s_ashr_i32 s13, s12, 31
	s_waitcnt lgkmcnt(0)
	v_lshl_add_u64 v[38:39], s[4:5], 0, v[34:35]
	v_cndmask_b32_e32 v4, v2, v4, vcc
	v_lshlrev_b32_e32 v46, 2, v4
	v_xor_b32_e32 v4, 4, v2
	v_cmp_lt_i32_e32 vcc, v4, v3
	s_lshl_b64 s[4:5], s[12:13], 12
	s_add_u32 s4, s6, s4
	v_cndmask_b32_e32 v4, v2, v4, vcc
	v_lshlrev_b32_e32 v48, 2, v4
	v_xor_b32_e32 v4, 8, v2
	v_cmp_lt_i32_e32 vcc, v4, v3
	v_mov_b32_e32 v37, v35
	s_addc_u32 s5, s7, s5
	v_cndmask_b32_e32 v4, v2, v4, vcc
	v_lshlrev_b32_e32 v49, 2, v4
	v_xor_b32_e32 v4, 16, v2
	v_cmp_lt_i32_e32 vcc, v4, v3
	s_ashr_i32 s15, s14, 31
	s_lshl_b64 s[18:19], s[14:15], 12
	v_cndmask_b32_e32 v4, v2, v4, vcc
	v_lshlrev_b32_e32 v50, 2, v4
	v_xor_b32_e32 v4, 32, v2
	v_cmp_lt_i32_e32 vcc, v4, v3
	s_movk_i32 s13, 0x1000
	s_mov_b32 s15, 0xf800000
	v_cndmask_b32_e32 v2, v2, v4, vcc
	v_lshlrev_b32_e32 v51, 2, v2
	v_lshl_add_u64 v[2:3], s[4:5], 0, v[36:37]
	s_mov_b64 s[4:5], 0x38000000
	v_lshl_add_u64 v[40:41], v[2:3], 0, s[4:5]
	v_mov_b32_e32 v37, 0x358637bd
	v_mov_b32_e32 v52, 0x260
	s_movk_i32 s20, 0x7fff
	v_mov_b32_e32 v53, 1
	s_mov_b32 s21, s12
